# hgrn_fin: group-norm weight loads issued with the first batch (1 round trip per item instead of 2)
# baseline (speedup 1.0000x reference)
.LBB0_223:
	v_mov_b32_e32 v0, v1
	s_add_i32 s21, s21, s81
	v_mbcnt_lo_u32_b32 v0, -1, v0
	v_mbcnt_hi_u32_b32 v0, -1, v0
	v_add_u32_e32 v0, s80, v0
	s_nop 0
	v_ashrrev_i32_e32 v6, 3, v0
	s_waitcnt lgkmcnt(0)
	v_add_u32_e32 v2, s20, v6
	v_ashrrev_i32_e32 v2, 2, v2
	v_ashrrev_i32_e32 v3, 31, v2
	v_lshlrev_b64 v[4:5], 9, v[2:3]
	v_lshlrev_b32_e32 v3, 7, v6
	v_and_b32_e32 v8, 0x180, v3
	v_lshlrev_b32_e32 v0, 4, v0
	v_mov_b64_e32 v[6:7], s[58:59]
	v_and_b32_e32 v22, 0x70, v0
	v_mad_i64_i32 v[2:3], s[24:25], v2, s31, v[6:7]
	v_lshlrev_b32_e32 v0, 1, v8
	v_lshl_add_u64 v[2:3], v[2:3], 0, v[0:1]
	v_lshlrev_b32_e32 v0, 1, v22
	v_or3_b32 v4, v4, v8, v22
	v_lshl_add_u64 v[2:3], v[2:3], 0, v[0:1]
	v_lshlrev_b64 v[6:7], 1, v[4:5]
	v_lshl_add_u64 v[20:21], v[2:3], 0, s[34:35]
	v_add_co_u32_e32 v2, vcc, s2, v2
	v_lshl_add_u64 v[32:33], v[4:5], 2, s[4:5]
	v_lshl_add_u64 v[4:5], s[22:23], 0, v[6:7]
	v_addc_co_u32_e32 v3, vcc, 0, v3, vcc
	global_load_dwordx4 v[8:11], v[4:5], off
	global_load_dwordx4 v[12:15], v[4:5], off offset:16
	v_cmp_lt_i32_e32 vcc, v227, v221
	global_load_dwordx4 v[16:19], v[2:3], off
	s_nop 0
	global_load_dwordx4 v[2:5], v[20:21], off offset:16
	v_cndmask_b32_e32 v20, v220, v227, vcc
	v_cmp_lt_i32_e32 vcc, v226, v221
	v_lshlrev_b32_e32 v70, 2, v20
	v_lshlrev_b32_e32 v0, 2, v22
	v_cndmask_b32_e32 v20, v220, v226, vcc
	v_cmp_lt_i32_e32 vcc, v235, v221
	v_lshlrev_b32_e32 v71, 2, v20
	v_lshl_add_u64 v[6:7], s[28:29], 0, v[6:7]
	v_cndmask_b32_e32 v20, v220, v235, vcc
	v_lshlrev_b32_e32 v72, 2, v20
	global_load_dwordx4 v[20:23], v[32:33], off offset:48
	global_load_dwordx4 v[24:27], v[32:33], off offset:32
	global_load_dwordx4 v[28:31], v[32:33], off offset:16
	s_nop 0
	global_load_dwordx4 v[32:35], v[32:33], off
	global_load_dwordx4 v[100:103], v0, s[26:27] offset:48
	global_load_dwordx4 v[104:107], v0, s[26:27] offset:32
	global_load_dwordx4 v[108:111], v0, s[26:27] offset:16
	global_load_dwordx4 v[112:115], v0, s[26:27]
	s_add_i32 s20, s20, s30
	s_cmpk_gt_i32 s21, 0x3ff
	s_waitcnt vmcnt(4)
	v_lshlrev_b32_e32 v36, 16, v15
	v_and_b32_e32 v37, 0xffff0000, v15
	s_waitcnt vmcnt(4)
	v_and_b32_e32 v55, 0xffff0000, v4
	v_lshlrev_b32_e32 v58, 16, v3
	v_and_b32_e32 v59, 0xffff0000, v3
	v_lshlrev_b32_e32 v54, 16, v4
	v_mul_f32_e32 v4, 0xbfb8aa3b, v54
	v_exp_f32_e32 v4, v4
	v_lshlrev_b32_e32 v62, 16, v19
	v_and_b32_e32 v63, 0xffff0000, v19
	s_waitcnt vmcnt(4)
	v_pk_add_f32 v[48:49], v[22:23], v[36:37]
	v_lshlrev_b32_e32 v22, 16, v14
	v_and_b32_e32 v23, 0xffff0000, v14
	v_pk_add_f32 v[14:15], v[20:21], v[22:23]
	s_nop 0
	s_nop 0
	s_nop 0
	s_nop 0
	v_mul_f32_e32 v0, 0xbfb8aa3b, v55
	v_exp_f32_e32 v0, v0
	v_add_f32_e32 v4, 1.0, v4
	v_rcp_f32_e32 v56, v4
	v_lshlrev_b32_e32 v66, 16, v17
	v_add_f32_e32 v0, 1.0, v0
	v_rcp_f32_e32 v57, v0
	v_mul_f32_e32 v0, 0xbfb8aa3b, v58
	v_exp_f32_e32 v0, v0
	v_and_b32_e32 v67, 0xffff0000, v17
	v_pk_mul_f32 v[54:55], v[56:57], v[54:55]
	v_lshlrev_b32_e32 v56, 16, v13
	v_add_f32_e32 v0, 1.0, v0
	v_rcp_f32_e32 v60, v0
	v_mul_f32_e32 v0, 0xbfb8aa3b, v59
	v_exp_f32_e32 v0, v0
	v_and_b32_e32 v57, 0xffff0000, v13
	s_waitcnt vmcnt(6)
	v_pk_add_f32 v[26:27], v[26:27], v[56:57]
	v_pk_mul_f32 v[52:53], v[14:15], v[14:15]
	v_add_f32_e32 v0, 1.0, v0
	v_rcp_f32_e32 v61, v0
	v_pk_mul_f32 v[56:57], v[26:27], v[26:27]
	v_pk_mul_f32 v[50:51], v[48:49], v[48:49]
	v_pk_mul_f32 v[58:59], v[60:61], v[58:59]
	v_lshlrev_b32_e32 v60, 16, v12
	v_and_b32_e32 v61, 0xffff0000, v12
	v_pk_add_f32 v[12:13], v[24:25], v[60:61]
	v_lshlrev_b32_e32 v60, 16, v2
	v_mul_f32_e32 v0, 0xbfb8aa3b, v60
	v_exp_f32_e32 v0, v0
	v_and_b32_e32 v61, 0xffff0000, v2
	v_pk_mul_f32 v[24:25], v[12:13], v[12:13]
	v_add_f32_e32 v0, 1.0, v0
	v_rcp_f32_e32 v2, v0
	v_mul_f32_e32 v0, 0xbfb8aa3b, v61
	v_exp_f32_e32 v0, v0
	s_nop 0
	v_add_f32_e32 v0, 1.0, v0
	v_rcp_f32_e32 v3, v0
	v_mul_f32_e32 v0, 0xbfb8aa3b, v62
	v_exp_f32_e32 v0, v0
	v_pk_mul_f32 v[2:3], v[2:3], v[60:61]
	v_lshlrev_b32_e32 v60, 16, v11
	v_add_f32_e32 v0, 1.0, v0
	v_rcp_f32_e32 v64, v0
	v_mul_f32_e32 v0, 0xbfb8aa3b, v63
	v_exp_f32_e32 v0, v0
	v_and_b32_e32 v61, 0xffff0000, v11
	s_waitcnt vmcnt(5)
	v_pk_add_f32 v[30:31], v[30:31], v[60:61]
	v_add_f32_e32 v0, 1.0, v0
	v_rcp_f32_e32 v65, v0
	v_pk_mul_f32 v[60:61], v[30:31], v[30:31]
	v_pk_mul_f32 v[62:63], v[64:65], v[62:63]
	v_lshlrev_b32_e32 v64, 16, v10
	v_and_b32_e32 v65, 0xffff0000, v10
	v_pk_add_f32 v[10:11], v[28:29], v[64:65]
	v_lshlrev_b32_e32 v64, 16, v18
	v_mul_f32_e32 v0, 0xbfb8aa3b, v64
	v_exp_f32_e32 v0, v0
	v_and_b32_e32 v65, 0xffff0000, v18
	v_pk_mul_f32 v[28:29], v[10:11], v[10:11]
	v_add_f32_e32 v0, 1.0, v0
	v_rcp_f32_e32 v18, v0
	v_mul_f32_e32 v0, 0xbfb8aa3b, v65
	v_exp_f32_e32 v0, v0
	s_nop 0
	v_add_f32_e32 v0, 1.0, v0
	v_rcp_f32_e32 v19, v0
	v_mul_f32_e32 v0, 0xbfb8aa3b, v66
	v_exp_f32_e32 v0, v0
	v_pk_mul_f32 v[18:19], v[18:19], v[64:65]
	v_lshlrev_b32_e32 v64, 16, v9
	v_add_f32_e32 v0, 1.0, v0
	v_rcp_f32_e32 v68, v0
	v_mul_f32_e32 v0, 0xbfb8aa3b, v67
	v_exp_f32_e32 v0, v0
	v_and_b32_e32 v65, 0xffff0000, v9
	s_waitcnt vmcnt(4)
	v_pk_add_f32 v[34:35], v[34:35], v[64:65]
	v_add_f32_e32 v0, 1.0, v0
	v_rcp_f32_e32 v69, v0
	v_pk_mul_f32 v[64:65], v[34:35], v[34:35]
	v_pk_mul_f32 v[66:67], v[68:69], v[66:67]
	v_lshlrev_b32_e32 v68, 16, v8
	v_and_b32_e32 v69, 0xffff0000, v8
	v_pk_add_f32 v[8:9], v[32:33], v[68:69]
	v_lshlrev_b32_e32 v68, 16, v16
	v_mul_f32_e32 v0, 0xbfb8aa3b, v68
	v_exp_f32_e32 v0, v0
	v_and_b32_e32 v69, 0xffff0000, v16
	v_pk_mul_f32 v[32:33], v[8:9], v[8:9]
	v_add_f32_e32 v0, 1.0, v0
	v_rcp_f32_e32 v16, v0
	v_mul_f32_e32 v0, 0xbfb8aa3b, v69
	v_exp_f32_e32 v0, v0
	s_nop 0
	v_add_f32_e32 v0, 1.0, v0
	v_rcp_f32_e32 v17, v0
	v_add_f32_e32 v0, v32, v33
	v_add_f32_e32 v0, v64, v0
	v_add_f32_e32 v0, v65, v0
	v_add_f32_e32 v0, v28, v0
	v_add_f32_e32 v0, v29, v0
	v_add_f32_e32 v0, v60, v0
	v_add_f32_e32 v0, v61, v0
	v_add_f32_e32 v0, v24, v0
	v_add_f32_e32 v0, v25, v0
	v_add_f32_e32 v0, v56, v0
	v_add_f32_e32 v0, v57, v0
	v_add_f32_e32 v0, v52, v0
	v_add_f32_e32 v0, v53, v0
	v_add_f32_e32 v0, v50, v0
	v_add_f32_e32 v0, v51, v0
	ds_bpermute_b32 v4, v70, v0
	v_pk_mul_f32 v[16:17], v[16:17], v[68:69]
	s_waitcnt lgkmcnt(0)
	v_add_f32_e32 v0, v0, v4
	ds_bpermute_b32 v4, v71, v0
	s_waitcnt lgkmcnt(0)
	v_add_f32_e32 v0, v0, v4
	ds_bpermute_b32 v4, v72, v0
	s_waitcnt lgkmcnt(0)
	v_add_f32_e32 v0, v0, v4
	v_fmamk_f32 v0, v0, 0x3c000000, v187
	v_cmp_gt_f32_e32 vcc, s82, v0
	v_mul_f32_e32 v4, 0x4b800000, v0
	s_nop 0
	v_cndmask_b32_e32 v0, v0, v4, vcc
	v_rsq_f32_e32 v0, v0
	s_nop 0
	v_mul_f32_e32 v4, 0x45800000, v0
	v_cndmask_b32_e32 v0, v0, v4, vcc
	v_pk_mul_f32 v[12:13], v[12:13], v[0:1] op_sel_hi:[1,0]
	v_pk_mul_f32 v[8:9], v[8:9], v[0:1] op_sel_hi:[1,0]
	s_waitcnt vmcnt(0)
	v_mov_b32_e32 v20, v100
	v_mov_b32_e32 v21, v101
	v_mov_b32_e32 v22, v102
	v_mov_b32_e32 v23, v103
	v_mov_b32_e32 v36, v104
	v_mov_b32_e32 v37, v105
	v_mov_b32_e32 v38, v106
	v_mov_b32_e32 v39, v107
	v_mov_b32_e32 v40, v108
	v_mov_b32_e32 v41, v109
	v_mov_b32_e32 v42, v110
	v_mov_b32_e32 v43, v111
	v_mov_b32_e32 v44, v112
	v_mov_b32_e32 v45, v113
	v_mov_b32_e32 v46, v114
	v_mov_b32_e32 v47, v115
	v_pk_mul_f32 v[12:13], v[36:37], v[12:13]
	s_waitcnt vmcnt(0)
	v_pk_mul_f32 v[8:9], v[44:45], v[8:9]
	v_pk_mul_f32 v[12:13], v[2:3], v[12:13]
	v_pk_mul_f32 v[2:3], v[34:35], v[0:1] op_sel_hi:[1,0]
	v_pk_mul_f32 v[8:9], v[16:17], v[8:9]
	v_pk_mul_f32 v[2:3], v[46:47], v[2:3]
	s_nop 0
	v_pk_mul_f32 v[16:17], v[66:67], v[2:3]
	v_pk_mul_f32 v[2:3], v[26:27], v[0:1] op_sel_hi:[1,0]
	s_nop 0
	v_pk_mul_f32 v[2:3], v[38:39], v[2:3]
	s_nop 0
	v_pk_mul_f32 v[24:25], v[58:59], v[2:3]
	v_pk_mul_f32 v[2:3], v[10:11], v[0:1] op_sel_hi:[1,0]
	s_nop 0
	v_pk_mul_f32 v[2:3], v[40:41], v[2:3]
	s_nop 0
	v_pk_mul_f32 v[10:11], v[18:19], v[2:3]
	v_pk_mul_f32 v[2:3], v[14:15], v[0:1] op_sel_hi:[1,0]
	s_nop 0
	v_pk_mul_f32 v[2:3], v[20:21], v[2:3]
	v_pk_mul_f32 v[20:21], v[48:49], v[0:1] op_sel_hi:[1,0]
	v_pk_mul_f32 v[14:15], v[54:55], v[2:3]
	v_pk_mul_f32 v[2:3], v[30:31], v[0:1] op_sel_hi:[1,0]
	v_pk_mul_f32 v[20:21], v[22:23], v[20:21]
	v_pk_mul_f32 v[2:3], v[42:43], v[2:3]
	s_nop 0
	v_pk_mul_f32 v[18:19], v[62:63], v[2:3]
	v_lshlrev_b32_e32 v2, 16, v5
	v_and_b32_e32 v3, 0xffff0000, v5
	v_mul_f32_e32 v4, 0xbfb8aa3b, v2
	v_mul_f32_e32 v0, 0xbfb8aa3b, v3
	v_exp_f32_e32 v4, v4
	v_exp_f32_e32 v0, v0
	v_add_f32_e32 v4, 1.0, v4
	v_add_f32_e32 v0, 1.0, v0
	v_rcp_f32_e32 v4, v4
	v_rcp_f32_e32 v5, v0
	s_nop 0
	v_pk_mul_f32 v[2:3], v[4:5], v[2:3]
	s_nop 0
	v_pk_mul_f32 v[20:21], v[2:3], v[20:21]
	v_cvt_pk_bf16_f32 v2, v8, v9
	v_cvt_pk_bf16_f32 v3, v16, v17
	v_cvt_pk_bf16_f32 v4, v10, v11
	v_cvt_pk_bf16_f32 v5, v18, v19
	global_store_dwordx4 v[6:7], v[2:5], off
	s_nop 1
	v_cvt_pk_bf16_f32 v2, v12, v13
	v_cvt_pk_bf16_f32 v3, v24, v25
	v_cvt_pk_bf16_f32 v4, v14, v15
	v_cvt_pk_bf16_f32 v5, v20, v21
	global_store_dwordx4 v[6:7], v[2:5], off offset:16
	s_cbranch_scc0 .LBB0_223

.Lattn_static:
	s_waitcnt lgkmcnt(0)
	ds_read_b32 v2, v196 offset:4
	v_readlane_b32 s99, v255, 12
	s_waitcnt lgkmcnt(0)
	v_readfirstlane_b32 s24, v2
	s_nop 3
	s_and_b32 s25, s99, 7
	s_lshl_b32 s25, s25, 6
	s_lshr_b32 s26, s99, 3
	s_or_b32 s25, s25, s26
	s_add_i32 s25, s25, 0x100
	s_cmpk_lt_u32 s99, 0x100
	s_cselect_b32 s26, 0, 1
	s_add_i32 s26, s26, s24
	s_add_i32 s24, s24, 1
	s_cmp_eq_u32 s26, 1
	s_cselect_b32 s98, s25, 0x300
	s_cmp_eq_u32 s26, 0
	s_cselect_b32 s98, s99, s98
	v_readlane_b32 vcc_hi, v255, 30
	s_nop 3
	s_cmpk_lt_u32 s99, 0x100
	s_cbranch_scc1 .Lcv_no
	s_cmp_eq_u32 vcc_hi, 0
	s_cbranch_scc1 .Lcv_no
	s_cmp_lt_u32 s26, 2
	s_cbranch_scc1 .Lcv_no
	s_cmp_gt_u32 s26, 9
	s_cbranch_scc1 .Lcv_no
	s_sub_u32 vcc_lo, s26, 2
	s_lshl_b32 vcc_lo, vcc_lo, 8
	s_add_u32 vcc_lo, s99, vcc_lo
	s_add_u32 vcc_lo, vcc_lo, 0x460
	s_cmpk_ge_u32 vcc_lo, 0xd60
	s_cbranch_scc1 .Lcv_no
	s_mov_b32 s98, vcc_lo
	s_branch .Lcv_keep

.LBB0_258:
	s_and_b64 vcc, exec, s[4:5]
	s_cbranch_vccz .LBB0_260
	v_ashrrev_i32_e32 v0, 3, v236
	s_waitcnt lgkmcnt(0)
	v_lshl_add_u32 v2, s25, 5, v0
	v_ashrrev_i32_e32 v2, 2, v2
	v_ashrrev_i32_e32 v3, 31, v2
	v_lshlrev_b64 v[4:5], 9, v[2:3]
	v_lshlrev_b32_e32 v0, 7, v0
	v_lshlrev_b32_e32 v3, 4, v236
	v_readlane_b32 s36, v252, 4
	v_and_b32_e32 v0, 0x180, v0
	v_and_b32_e32 v16, 0x70, v3
	v_readlane_b32 s4, v255, 8
	v_readlane_b32 s50, v252, 18
	v_readlane_b32 s51, v252, 19
	v_or3_b32 v4, v4, v0, v16
	v_readlane_b32 s5, v255, 9
	v_mov_b64_e32 v[6:7], s[50:51]
	v_lshlrev_b32_e32 v0, 1, v0
	v_lshl_add_u64 v[18:19], v[4:5], 2, s[4:5]
	v_mad_i64_i32 v[2:3], s[4:5], v2, s2, v[6:7]
	v_readlane_b32 s4, v255, 15
	v_lshl_add_u64 v[2:3], v[2:3], 0, v[0:1]
	v_lshlrev_b64 v[42:43], 1, v[4:5]
	v_readlane_b32 s5, v255, 16
	v_lshlrev_b32_e32 v0, 1, v16
	v_lshl_add_u64 v[2:3], v[2:3], 0, v[0:1]
	v_lshl_add_u64 v[4:5], s[4:5], 0, v[42:43]
	s_mov_b64 s[4:5], 0x6c26000
	s_mov_b32 s1, 0x6c26000
	v_lshl_add_u64 v[14:15], v[2:3], 0, s[4:5]
	v_add_co_u32_e32 v2, vcc, s1, v2
	global_load_dwordx4 v[10:13], v[4:5], off
	global_load_dwordx4 v[38:41], v[4:5], off offset:16
	v_addc_co_u32_e32 v3, vcc, 0, v3, vcc
	global_load_dwordx4 v[6:9], v[2:3], off
	s_nop 0
	global_load_dwordx4 v[2:5], v[14:15], off offset:16
	v_lshlrev_b32_e32 v26, 2, v16
	global_load_dwordx4 v[14:17], v[18:19], off offset:48
	global_load_dwordx4 v[58:61], v[18:19], off offset:32
	global_load_dwordx4 v[34:37], v[18:19], off offset:16
	global_load_dwordx4 v[30:33], v[18:19], off
	v_readlane_b32 s4, v255, 17
	v_readlane_b32 s5, v255, 18
	v_cmp_lt_i32_e32 vcc, v227, v221
	v_readlane_b32 s37, v252, 5
	v_readlane_b32 s38, v252, 6
	v_cndmask_b32_e32 v0, v220, v227, vcc
	v_lshlrev_b32_e32 v65, 2, v0
	v_cmp_lt_i32_e32 vcc, v226, v221
	v_readlane_b32 s39, v252, 7
	v_readlane_b32 s40, v252, 8
	v_cndmask_b32_e32 v0, v220, v226, vcc
	v_lshlrev_b32_e32 v64, 2, v0
	v_cmp_lt_i32_e32 vcc, v235, v221
	v_readlane_b32 s41, v252, 9
	v_readlane_b32 s42, v252, 10
	v_cndmask_b32_e32 v0, v220, v235, vcc
	v_lshlrev_b32_e32 v0, 2, v0
	v_readlane_b32 s43, v252, 11
	v_readlane_b32 s44, v252, 12
	v_readlane_b32 s45, v252, 13
	v_readlane_b32 s46, v252, 14
	v_readlane_b32 s47, v252, 15
	v_readlane_b32 s48, v252, 16
	v_readlane_b32 s49, v252, 17
	global_load_dwordx4 v[100:103], v26, s[4:5] offset:48
	global_load_dwordx4 v[104:107], v26, s[4:5] offset:32
	global_load_dwordx4 v[108:111], v26, s[4:5] offset:16
	global_load_dwordx4 v[112:115], v26, s[4:5]
	s_waitcnt vmcnt(4)
	v_lshlrev_b32_e32 v18, 16, v41
	v_and_b32_e32 v19, 0xffff0000, v41
	s_waitcnt vmcnt(5)
	v_lshlrev_b32_e32 v62, 16, v9
	s_waitcnt vmcnt(4)
	v_lshlrev_b32_e32 v50, 16, v4
	v_and_b32_e32 v51, 0xffff0000, v4
	v_mul_f32_e32 v4, 0xbfb8aa3b, v50
	v_exp_f32_e32 v4, v4
	v_lshlrev_b32_e32 v54, 16, v3
	v_and_b32_e32 v55, 0xffff0000, v3
	v_mul_f32_e32 v3, 0xbfb8aa3b, v54
	v_add_f32_e32 v4, 1.0, v4
	v_rcp_f32_e32 v52, v4
	v_mul_f32_e32 v4, 0xbfb8aa3b, v51
	v_exp_f32_e32 v4, v4
	v_exp_f32_e32 v3, v3
	v_and_b32_e32 v63, 0xffff0000, v9
	s_waitcnt vmcnt(4)
	v_pk_add_f32 v[44:45], v[16:17], v[18:19]
	v_add_f32_e32 v4, 1.0, v4
	v_rcp_f32_e32 v53, v4
	v_add_f32_e32 v3, 1.0, v3
	v_mul_f32_e32 v4, 0xbfb8aa3b, v62
	v_exp_f32_e32 v4, v4
	v_pk_mul_f32 v[50:51], v[52:53], v[50:51]
	v_lshlrev_b32_e32 v52, 16, v39
	v_and_b32_e32 v53, 0xffff0000, v39
	s_waitcnt vmcnt(4)
	v_pk_add_f32 v[52:53], v[60:61], v[52:53]
	v_rcp_f32_e32 v60, v3
	v_mul_f32_e32 v3, 0xbfb8aa3b, v55
	v_exp_f32_e32 v3, v3
	v_add_f32_e32 v4, 1.0, v4
	v_rcp_f32_e32 v66, v4
	v_mul_f32_e32 v4, 0xbfb8aa3b, v63
	v_add_f32_e32 v3, 1.0, v3
	v_rcp_f32_e32 v61, v3
	v_exp_f32_e32 v4, v4
	v_lshlrev_b32_e32 v16, 16, v40
	v_and_b32_e32 v17, 0xffff0000, v40
	v_pk_mul_f32 v[54:55], v[60:61], v[54:55]
	v_lshlrev_b32_e32 v60, 16, v38
	v_and_b32_e32 v61, 0xffff0000, v38
	v_pk_add_f32 v[38:39], v[58:59], v[60:61]
	v_lshlrev_b32_e32 v58, 16, v2
	v_and_b32_e32 v59, 0xffff0000, v2
	v_mul_f32_e32 v2, 0xbfb8aa3b, v58
	v_mul_f32_e32 v3, 0xbfb8aa3b, v59
	v_exp_f32_e32 v2, v2
	v_exp_f32_e32 v3, v3
	v_add_f32_e32 v4, 1.0, v4
	v_rcp_f32_e32 v67, v4
	v_add_f32_e32 v2, 1.0, v2
	v_add_f32_e32 v3, 1.0, v3
	v_rcp_f32_e32 v2, v2
	v_rcp_f32_e32 v3, v3
	v_pk_mul_f32 v[62:63], v[66:67], v[62:63]
	v_lshlrev_b32_e32 v66, 16, v12
	v_and_b32_e32 v67, 0xffff0000, v12
	v_pk_mul_f32 v[58:59], v[2:3], v[58:59]
	v_lshlrev_b32_e32 v2, 16, v13
	v_and_b32_e32 v3, 0xffff0000, v13
	s_waitcnt vmcnt(4)
	v_pk_add_f32 v[12:13], v[34:35], v[66:67]
	v_lshlrev_b32_e32 v66, 16, v8
	v_mul_f32_e32 v4, 0xbfb8aa3b, v66
	v_exp_f32_e32 v4, v4
	v_and_b32_e32 v67, 0xffff0000, v8
	v_pk_add_f32 v[40:41], v[14:15], v[16:17]
	s_nop 0
	s_nop 0
	s_nop 0
	s_nop 0
	s_nop 0
	v_add_f32_e32 v4, 1.0, v4
	v_rcp_f32_e32 v8, v4
	v_mul_f32_e32 v4, 0xbfb8aa3b, v67
	v_exp_f32_e32 v4, v4
	v_lshlrev_b32_e32 v68, 16, v7
	v_and_b32_e32 v69, 0xffff0000, v7
	v_pk_mul_f32 v[34:35], v[12:13], v[12:13]
	v_add_f32_e32 v4, 1.0, v4
	v_rcp_f32_e32 v9, v4
	v_mul_f32_e32 v4, 0xbfb8aa3b, v68
	v_exp_f32_e32 v4, v4
	v_pk_add_f32 v[2:3], v[36:37], v[2:3]
	v_pk_mul_f32 v[8:9], v[8:9], v[66:67]
	v_lshlrev_b32_e32 v66, 16, v11
	v_add_f32_e32 v4, 1.0, v4
	v_rcp_f32_e32 v70, v4
	v_mul_f32_e32 v4, 0xbfb8aa3b, v69
	v_exp_f32_e32 v4, v4
	v_and_b32_e32 v67, 0xffff0000, v11
	s_waitcnt vmcnt(4)
	v_pk_add_f32 v[32:33], v[32:33], v[66:67]
	v_pk_mul_f32 v[36:37], v[2:3], v[2:3]
	v_add_f32_e32 v4, 1.0, v4
	v_rcp_f32_e32 v71, v4
	v_pk_mul_f32 v[66:67], v[32:33], v[32:33]
	v_pk_mul_f32 v[60:61], v[38:39], v[38:39]
	v_pk_mul_f32 v[56:57], v[52:53], v[52:53]
	v_pk_mul_f32 v[68:69], v[70:71], v[68:69]
	v_lshlrev_b32_e32 v70, 16, v10
	v_and_b32_e32 v71, 0xffff0000, v10
	v_pk_add_f32 v[10:11], v[30:31], v[70:71]
	v_lshlrev_b32_e32 v70, 16, v6
	v_mul_f32_e32 v4, 0xbfb8aa3b, v70
	v_exp_f32_e32 v4, v4
	v_and_b32_e32 v71, 0xffff0000, v6
	v_pk_mul_f32 v[30:31], v[10:11], v[10:11]
	v_pk_mul_f32 v[48:49], v[40:41], v[40:41]
	v_add_f32_e32 v4, 1.0, v4
	v_rcp_f32_e32 v6, v4
	v_mul_f32_e32 v4, 0xbfb8aa3b, v71
	v_exp_f32_e32 v4, v4
	v_pk_mul_f32 v[46:47], v[44:45], v[44:45]
	v_readlane_b32 s4, v252, 22
	v_readlane_b32 s5, v252, 23
	v_add_f32_e32 v4, 1.0, v4
	v_rcp_f32_e32 v7, v4
	v_add_f32_e32 v4, v30, v31
	v_add_f32_e32 v4, v66, v4
	v_add_f32_e32 v4, v67, v4
	v_add_f32_e32 v4, v34, v4
	v_add_f32_e32 v4, v35, v4
	v_add_f32_e32 v4, v36, v4
	v_add_f32_e32 v4, v37, v4
	v_add_f32_e32 v4, v60, v4
	v_add_f32_e32 v4, v61, v4
	v_add_f32_e32 v4, v56, v4
	v_add_f32_e32 v4, v57, v4
	v_add_f32_e32 v4, v48, v4
	v_add_f32_e32 v4, v49, v4
	v_add_f32_e32 v4, v46, v4
	v_add_f32_e32 v4, v47, v4
	ds_bpermute_b32 v30, v65, v4
	v_pk_mul_f32 v[6:7], v[6:7], v[70:71]
	s_waitcnt lgkmcnt(0)
	v_add_f32_e32 v4, v4, v30
	ds_bpermute_b32 v30, v64, v4
	s_waitcnt lgkmcnt(0)
	v_add_f32_e32 v4, v4, v30
	ds_bpermute_b32 v0, v0, v4
	s_waitcnt lgkmcnt(0)
	v_add_f32_e32 v0, v4, v0
	v_fmamk_f32 v0, v0, 0x3c000000, v187
	v_cmp_gt_f32_e32 vcc, s82, v0
	v_mul_f32_e32 v4, 0x4b800000, v0
	s_nop 0
	v_cndmask_b32_e32 v0, v0, v4, vcc
	v_rsq_f32_e32 v0, v0
	s_nop 0
	v_mul_f32_e32 v4, 0x45800000, v0
	v_cndmask_b32_e32 v0, v0, v4, vcc
	v_pk_mul_f32 v[12:13], v[12:13], v[0:1] op_sel_hi:[1,0]
	v_pk_mul_f32 v[10:11], v[10:11], v[0:1] op_sel_hi:[1,0]
	s_waitcnt vmcnt(0)
	v_mov_b32_e32 v14, v100
	v_mov_b32_e32 v15, v101
	v_mov_b32_e32 v16, v102
	v_mov_b32_e32 v17, v103
	v_mov_b32_e32 v22, v104
	v_mov_b32_e32 v23, v105
	v_mov_b32_e32 v24, v106
	v_mov_b32_e32 v25, v107
	v_mov_b32_e32 v18, v108
	v_mov_b32_e32 v19, v109
	v_mov_b32_e32 v20, v110
	v_mov_b32_e32 v21, v111
	v_mov_b32_e32 v26, v112
	v_mov_b32_e32 v27, v113
	v_mov_b32_e32 v28, v114
	v_mov_b32_e32 v29, v115
	v_pk_mul_f32 v[12:13], v[18:19], v[12:13]
	v_pk_mul_f32 v[2:3], v[2:3], v[0:1] op_sel_hi:[1,0]
	s_waitcnt vmcnt(0)
	v_pk_mul_f32 v[10:11], v[26:27], v[10:11]
	v_pk_mul_f32 v[8:9], v[8:9], v[12:13]
	v_pk_mul_f32 v[12:13], v[40:41], v[0:1] op_sel_hi:[1,0]
	v_pk_mul_f32 v[2:3], v[20:21], v[2:3]
	v_pk_mul_f32 v[6:7], v[6:7], v[10:11]
	v_pk_mul_f32 v[10:11], v[38:39], v[0:1] op_sel_hi:[1,0]
	v_pk_mul_f32 v[12:13], v[14:15], v[12:13]
	v_pk_mul_f32 v[14:15], v[62:63], v[2:3]
	v_lshlrev_b32_e32 v2, 16, v5
	v_and_b32_e32 v3, 0xffff0000, v5
	v_pk_mul_f32 v[10:11], v[22:23], v[10:11]
	v_pk_mul_f32 v[22:23], v[32:33], v[0:1] op_sel_hi:[1,0]
	v_pk_mul_f32 v[26:27], v[52:53], v[0:1] op_sel_hi:[1,0]
	v_mul_f32_e32 v4, 0xbfb8aa3b, v2
	v_pk_mul_f32 v[18:19], v[44:45], v[0:1] op_sel_hi:[1,0]
	v_mul_f32_e32 v0, 0xbfb8aa3b, v3
	v_exp_f32_e32 v4, v4
	v_exp_f32_e32 v0, v0
	v_pk_mul_f32 v[22:23], v[28:29], v[22:23]
	v_pk_mul_f32 v[24:25], v[24:25], v[26:27]
	v_add_f32_e32 v4, 1.0, v4
	v_add_f32_e32 v0, 1.0, v0
	v_rcp_f32_e32 v4, v4
	v_rcp_f32_e32 v5, v0
	v_pk_mul_f32 v[22:23], v[68:69], v[22:23]
	v_pk_mul_f32 v[16:17], v[16:17], v[18:19]
	v_pk_mul_f32 v[10:11], v[58:59], v[10:11]
	v_pk_mul_f32 v[2:3], v[4:5], v[2:3]
	v_pk_mul_f32 v[24:25], v[54:55], v[24:25]
	v_pk_mul_f32 v[12:13], v[50:51], v[12:13]
	v_pk_mul_f32 v[16:17], v[2:3], v[16:17]
	v_lshl_add_u64 v[18:19], s[4:5], 0, v[42:43]
	v_cvt_pk_bf16_f32 v2, v6, v7
	v_cvt_pk_bf16_f32 v3, v22, v23
	v_cvt_pk_bf16_f32 v4, v8, v9
	v_cvt_pk_bf16_f32 v5, v14, v15
	global_store_dwordx4 v[18:19], v[2:5], off
	s_nop 1
	v_cvt_pk_bf16_f32 v2, v10, v11
	v_cvt_pk_bf16_f32 v3, v24, v25
	v_cvt_pk_bf16_f32 v4, v12, v13
	v_cvt_pk_bf16_f32 v5, v16, v17
	global_store_dwordx4 v[18:19], v[2:5], off offset:16
